# v103 + merged vmcnt/lgkmcnt wait pair at one attention pair barrier (wait consolidation)
# baseline (speedup 1.0000x reference)
.LBB0_413:
	s_waitcnt vmcnt(0) lgkmcnt(0)
	s_barrier
	s_mov_b64 s[10:11], 0
	s_cmp_eq_u64 s[6:7], 0
	s_mov_b64 s[20:21], 0
	s_cbranch_scc1 .LBB0_415
	s_add_u32 s18, s6, -1
	s_addc_u32 s19, s7, -1
	s_not_b32 s14, s5
	s_ff1_i32_b64 s13, s[6:7]
	s_lshl_b32 s14, s14, 14
	s_and_b32 s14, s14, 0x8000
	s_lshl_b32 s16, s13, 19
	v_lshl_add_u64 v[54:55], v[158:159], 0, s[16:17]
	s_add_i32 s13, s15, s14
	v_lshl_add_u64 v[56:57], v[54:55], 0, s[84:85]
	s_add_i32 m0, s13, 0x4000
	v_lshl_add_u64 v[54:55], v[54:55], 0, s[86:87]
	global_load_lds_dwordx4 v[56:57], off
	s_add_i32 m0, s13, 0x6000
	s_and_b64 s[20:21], s[18:19], s[6:7]
	global_load_lds_dwordx4 v[54:55], off
